# opt6 plus nt (streaming) hints on the ph0 weight-transpose loads and stores
# baseline (speedup 1.0000x reference)
; __device__ __forceinline__ void titem_load(const TItem& t, TRegs& R, int lane) {
;     const int nblk = (t.N + 63) / 64, kb = t.item / nblk, nb = t.item % nblk, k0 = 64 * kb, n0 = 64 * nb;
;     const int rg = lane >> 4, c4 = lane & 15, nn = n0 + 4 * c4; const bool ok = nn < t.N;
; #pragma unroll
;     for (int i = 0; i < 8; ++i) { const float* p = t.W + (size_t)(k0 + 8 * i + 2 * rg) * t.N + nn;
;         R.v0[i] = ok ? *(const f32x4*)p : (f32x4){0.f, 0.f, 0.f, 0.f}; R.v1[i] = ok ? *(const f32x4*)(p + t.N) : (f32x4){0.f, 0.f, 0.f, 0.f}; }
; }
.LBB0_428:
	s_add_i32 s2, s4, 63
	s_lshr_b32 s2, s2, 6
	v_cvt_f32_i32_e32 v0, s2
	s_sext_i32_i16 s5, s34
	v_cvt_f32_i32_e32 v2, s5
	s_ashr_i32 s5, s5, 30
	v_rcp_iflag_f32_e32 v3, v0
	s_or_b32 s5, s5, 1
	v_lshrrev_b32_e32 v138, 3, v132
	v_and_b32_e32 v139, 6, v138
	v_mul_f32_e32 v3, v2, v3
	v_trunc_f32_e32 v3, v3
	v_fma_f32 v2, -v3, v0, v2
	v_cvt_i32_f32_e32 v3, v3
	v_cmp_ge_f32_e64 s[8:9], |v2|, v0
	s_and_b64 s[8:9], s[8:9], exec
	s_cselect_b32 s5, s5, 0
	v_readfirstlane_b32 s8, v3
	s_add_i32 s5, s8, s5
	s_sext_i32_i16 s8, s5
	s_mul_i32 s5, s5, s2
	s_sub_i32 s2, s34, s5
	v_lshlrev_b32_e32 v0, 2, v132
	s_sext_i32_i16 s2, s2
	v_and_b32_e32 v133, 60, v0
	v_mov_b32_e32 v2, v1
	v_mov_b32_e32 v3, v1
	v_lshl_or_b32 v68, s2, 6, v133
	v_mov_b32_e32 v0, v1
	v_mov_b64_e32 v[10:11], v[2:3]
	v_mov_b64_e32 v[6:7], v[2:3]
	v_cmp_gt_i32_e32 vcc, s4, v68
	v_lshl_or_b32 v71, s8, 6, v139
	v_ashrrev_i32_e32 v69, 31, v68
	v_mov_b64_e32 v[8:9], v[0:1]
	v_mov_b64_e32 v[4:5], v[0:1]
	s_and_saveexec_b64 s[8:9], vcc
	s_cbranch_execz .LBB0_430
	v_mul_hi_i32_i24_e32 v5, s4, v71
	v_mul_i32_i24_e32 v4, s4, v71
	v_lshl_add_u64 v[4:5], v[4:5], 2, s[6:7]
	s_mov_b32 s5, s91
	v_lshl_add_u64 v[4:5], v[68:69], 2, v[4:5]
	v_lshl_add_u64 v[6:7], s[4:5], 2, v[4:5]
	global_load_dwordx4 v[8:11], v[4:5], off nt
	s_nop 0
	global_load_dwordx4 v[4:7], v[6:7], off nt
.LBB0_430:
	s_or_b64 exec, exec, s[8:9]
	v_mov_b64_e32 v[18:19], v[2:3]
	v_mov_b64_e32 v[14:15], v[2:3]
	v_mov_b64_e32 v[16:17], v[0:1]
	v_mov_b64_e32 v[12:13], v[0:1]
	s_and_saveexec_b64 s[8:9], vcc
	s_cbranch_execz .LBB0_432
	v_or_b32_e32 v0, 8, v71
	v_mul_hi_i32_i24_e32 v3, s4, v0
	v_mul_i32_i24_e32 v2, s4, v0
	v_lshl_add_u64 v[2:3], v[2:3], 2, s[6:7]
	s_mov_b32 s5, s91
	v_lshl_add_u64 v[2:3], v[68:69], 2, v[2:3]
	v_lshl_add_u64 v[12:13], s[4:5], 2, v[2:3]
	global_load_dwordx4 v[16:19], v[2:3], off nt
	s_nop 0
	global_load_dwordx4 v[12:15], v[12:13], off nt
.LBB0_432:
	s_or_b64 exec, exec, s[8:9]
	v_mov_b32_e32 v2, v1
	v_mov_b32_e32 v3, v1
	v_mov_b32_e32 v0, v1
	v_mov_b64_e32 v[26:27], v[2:3]
	v_mov_b64_e32 v[22:23], v[2:3]
	v_mov_b64_e32 v[24:25], v[0:1]
	v_mov_b64_e32 v[20:21], v[0:1]
	s_and_saveexec_b64 s[8:9], vcc
	s_cbranch_execz .LBB0_434
	v_or_b32_e32 v20, 16, v71
	v_mul_hi_i32_i24_e32 v21, s4, v20
	v_mul_i32_i24_e32 v20, s4, v20
	v_lshl_add_u64 v[20:21], v[20:21], 2, s[6:7]
	s_mov_b32 s5, s91
	v_lshl_add_u64 v[20:21], v[68:69], 2, v[20:21]
	v_lshl_add_u64 v[22:23], s[4:5], 2, v[20:21]
	global_load_dwordx4 v[24:27], v[20:21], off nt
	s_nop 0
	global_load_dwordx4 v[20:23], v[22:23], off nt
.LBB0_434:
	s_or_b64 exec, exec, s[8:9]
	v_mov_b64_e32 v[34:35], v[2:3]
	v_mov_b64_e32 v[30:31], v[2:3]
	v_mov_b64_e32 v[32:33], v[0:1]
	v_mov_b64_e32 v[28:29], v[0:1]
	s_and_saveexec_b64 s[8:9], vcc
	s_cbranch_execz .LBB0_436
	v_or_b32_e32 v0, 24, v71
	v_mul_hi_i32_i24_e32 v3, s4, v0
	v_mul_i32_i24_e32 v2, s4, v0
	v_lshl_add_u64 v[2:3], v[2:3], 2, s[6:7]
	s_mov_b32 s5, s91
	v_lshl_add_u64 v[2:3], v[68:69], 2, v[2:3]
	v_lshl_add_u64 v[28:29], s[4:5], 2, v[2:3]
	global_load_dwordx4 v[32:35], v[2:3], off nt
	s_nop 0
	global_load_dwordx4 v[28:31], v[28:29], off nt
.LBB0_436:
	s_or_b64 exec, exec, s[8:9]
	v_mov_b32_e32 v2, v1
	v_mov_b32_e32 v3, v1
	v_mov_b32_e32 v0, v1
	v_mov_b64_e32 v[42:43], v[2:3]
	v_mov_b64_e32 v[38:39], v[2:3]
	v_mov_b64_e32 v[40:41], v[0:1]
	v_mov_b64_e32 v[36:37], v[0:1]
	s_and_saveexec_b64 s[8:9], vcc
	s_cbranch_execz .LBB0_438
	v_or_b32_e32 v36, 32, v71
	v_mul_hi_i32_i24_e32 v37, s4, v36
	v_mul_i32_i24_e32 v36, s4, v36
	v_lshl_add_u64 v[36:37], v[36:37], 2, s[6:7]
	s_mov_b32 s5, s91
	v_lshl_add_u64 v[36:37], v[68:69], 2, v[36:37]
	v_lshl_add_u64 v[38:39], s[4:5], 2, v[36:37]
	global_load_dwordx4 v[40:43], v[36:37], off nt
	s_nop 0
	global_load_dwordx4 v[36:39], v[38:39], off nt
.LBB0_438:
	s_or_b64 exec, exec, s[8:9]
	v_mov_b64_e32 v[50:51], v[2:3]
	v_mov_b64_e32 v[46:47], v[2:3]
	v_mov_b64_e32 v[48:49], v[0:1]
	v_mov_b64_e32 v[44:45], v[0:1]
	s_and_saveexec_b64 s[8:9], vcc
	s_cbranch_execz .LBB0_440
	v_or_b32_e32 v0, 40, v71
	v_mul_hi_i32_i24_e32 v3, s4, v0
	v_mul_i32_i24_e32 v2, s4, v0
	v_lshl_add_u64 v[2:3], v[2:3], 2, s[6:7]
	s_mov_b32 s5, s91
	v_lshl_add_u64 v[2:3], v[68:69], 2, v[2:3]
	v_lshl_add_u64 v[44:45], s[4:5], 2, v[2:3]
	global_load_dwordx4 v[48:51], v[2:3], off nt
	s_nop 0
	global_load_dwordx4 v[44:47], v[44:45], off nt
.LBB0_440:
	s_or_b64 exec, exec, s[8:9]
	v_mov_b32_e32 v2, v1
	v_mov_b32_e32 v3, v1
	v_mov_b32_e32 v0, v1
	v_mov_b64_e32 v[58:59], v[2:3]
	v_mov_b64_e32 v[54:55], v[2:3]
	v_mov_b64_e32 v[56:57], v[0:1]
	v_mov_b64_e32 v[52:53], v[0:1]
	s_and_saveexec_b64 s[8:9], vcc
	s_cbranch_execz .LBB0_442
	v_or_b32_e32 v52, 48, v71
	v_mul_hi_i32_i24_e32 v53, s4, v52
	v_mul_i32_i24_e32 v52, s4, v52
	v_lshl_add_u64 v[52:53], v[52:53], 2, s[6:7]
	s_mov_b32 s5, s91
	v_lshl_add_u64 v[52:53], v[68:69], 2, v[52:53]
	v_lshl_add_u64 v[54:55], s[4:5], 2, v[52:53]
	global_load_dwordx4 v[56:59], v[52:53], off nt
	s_nop 0
	global_load_dwordx4 v[52:55], v[54:55], off nt
.LBB0_442:
	s_or_b64 exec, exec, s[8:9]
	v_mov_b64_e32 v[66:67], v[2:3]
	v_mov_b64_e32 v[62:63], v[2:3]
	v_mov_b64_e32 v[64:65], v[0:1]
	v_mov_b64_e32 v[60:61], v[0:1]
	s_and_saveexec_b64 s[8:9], vcc
	s_cbranch_execz .LBB0_444
	v_or_b32_e32 v0, 56, v71
	v_mul_hi_i32_i24_e32 v3, s4, v0
	v_mul_i32_i24_e32 v2, s4, v0
	v_lshl_add_u64 v[2:3], v[2:3], 2, s[6:7]
	s_mov_b32 s5, s91
	v_lshl_add_u64 v[2:3], v[68:69], 2, v[2:3]
	v_lshl_add_u64 v[60:61], s[4:5], 2, v[2:3]
	global_load_dwordx4 v[64:67], v[2:3], off nt
	s_nop 0
	global_load_dwordx4 v[60:63], v[60:61], off nt

; __device__ __forceinline__ void titem_load(const TItem& t, TRegs& R, int lane) {
;     const int nblk = (t.N + 63) / 64, kb = t.item / nblk, nb = t.item % nblk, k0 = 64 * kb, n0 = 64 * nb;
;     const int rg = lane >> 4, c4 = lane & 15, nn = n0 + 4 * c4; const bool ok = nn < t.N;
; #pragma unroll
;     for (int i = 0; i < 8; ++i) { const float* p = t.W + (size_t)(k0 + 8 * i + 2 * rg) * t.N + nn;
;         R.v0[i] = ok ? *(const f32x4*)p : (f32x4){0.f, 0.f, 0.f, 0.f}; R.v1[i] = ok ? *(const f32x4*)(p + t.N) : (f32x4){0.f, 0.f, 0.f, 0.f}; }
; }
; __device__ __forceinline__ void phase_prologue(const PT a, float* ldsf, int lane, int wave, int gw, int ngw) {
;     ...
;         int it = gw; TItem cur = decode_item(a, ws, it); TRegs R; titem_load(cur, R, lane);
;         for (;;) {
;             const int nx = it + ngw; const bool more = nx < NIT;
;             TItem nxt = cur; TRegs R2 = R;
;             if (more) { nxt = decode_item(a, ws, nx); titem_load(nxt, R2, lane); }
.LBB0_486:
	s_add_i32 s12, s90, 63
	s_lshr_b32 s16, s12, 6
	v_cvt_f32_i32_e32 v0, s16
	s_sext_i32_i16 s12, s37
	v_cvt_f32_i32_e32 v2, s12
	s_ashr_i32 s12, s12, 30
	v_rcp_iflag_f32_e32 v3, v0
	s_or_b32 s17, s12, 1
	v_mul_f32_e32 v3, v2, v3
	v_trunc_f32_e32 v3, v3
	v_fma_f32 v2, -v3, v0, v2
	v_cvt_i32_f32_e32 v3, v3
	v_cmp_ge_f32_e64 s[12:13], |v2|, v0
	s_and_b64 s[12:13], s[12:13], exec
	s_cselect_b32 s12, s17, 0
	v_readfirstlane_b32 s13, v3
	s_add_i32 s12, s13, s12
	s_sext_i32_i16 s13, s12
	s_mul_i32 s12, s12, s16
	s_sub_i32 s12, s37, s12
	s_sext_i32_i16 s12, s12
	v_mov_b32_e32 v2, v1
	v_mov_b32_e32 v3, v1
	v_lshl_or_b32 v136, s12, 6, v133
	v_mov_b32_e32 v0, v1
	v_mov_b64_e32 v[70:71], v[2:3]
	v_mov_b64_e32 v[74:75], v[2:3]
	v_cmp_gt_i32_e32 vcc, s90, v136
	v_lshl_or_b32 v135, s13, 6, v139
	v_ashrrev_i32_e32 v137, 31, v136
	v_mov_b64_e32 v[68:69], v[0:1]
	v_mov_b64_e32 v[72:73], v[0:1]
	s_and_saveexec_b64 s[12:13], vcc
	s_cbranch_execz .LBB0_488
	v_mul_hi_i32_i24_e32 v69, s90, v135
	v_mul_i32_i24_e32 v68, s90, v135
	v_lshl_add_u64 v[68:69], v[68:69], 2, s[14:15]
	v_lshl_add_u64 v[68:69], v[136:137], 2, v[68:69]
	v_lshl_add_u64 v[72:73], s[90:91], 2, v[68:69]
	global_load_dwordx4 v[68:71], v[68:69], off nt
	s_nop 0
	global_load_dwordx4 v[72:75], v[72:73], off nt
.LBB0_488:
	s_or_b64 exec, exec, s[12:13]
	v_mov_b64_e32 v[78:79], v[2:3]
	v_mov_b64_e32 v[82:83], v[2:3]
	v_mov_b64_e32 v[76:77], v[0:1]
	v_mov_b64_e32 v[80:81], v[0:1]
	s_and_saveexec_b64 s[12:13], vcc
	s_cbranch_execz .LBB0_490
	v_or_b32_e32 v0, 8, v135
	v_mul_hi_i32_i24_e32 v3, s90, v0
	v_mul_i32_i24_e32 v2, s90, v0
	v_lshl_add_u64 v[2:3], v[2:3], 2, s[14:15]
	v_lshl_add_u64 v[2:3], v[136:137], 2, v[2:3]
	v_lshl_add_u64 v[80:81], s[90:91], 2, v[2:3]
	global_load_dwordx4 v[76:79], v[2:3], off nt
	s_nop 0
	global_load_dwordx4 v[80:83], v[80:81], off nt
.LBB0_490:
	s_or_b64 exec, exec, s[12:13]
	v_mov_b32_e32 v2, v1
	v_mov_b32_e32 v3, v1
	v_mov_b32_e32 v0, v1
	v_mov_b64_e32 v[86:87], v[2:3]
	v_mov_b64_e32 v[90:91], v[2:3]
	v_mov_b64_e32 v[84:85], v[0:1]
	v_mov_b64_e32 v[88:89], v[0:1]
	s_and_saveexec_b64 s[12:13], vcc
	s_cbranch_execz .LBB0_492
	v_or_b32_e32 v84, 16, v135
	v_mul_hi_i32_i24_e32 v85, s90, v84
	v_mul_i32_i24_e32 v84, s90, v84
	v_lshl_add_u64 v[84:85], v[84:85], 2, s[14:15]
	v_lshl_add_u64 v[84:85], v[136:137], 2, v[84:85]
	v_lshl_add_u64 v[88:89], s[90:91], 2, v[84:85]
	global_load_dwordx4 v[84:87], v[84:85], off nt
	s_nop 0
	global_load_dwordx4 v[88:91], v[88:89], off nt
.LBB0_492:
	s_or_b64 exec, exec, s[12:13]
	v_mov_b64_e32 v[94:95], v[2:3]
	v_mov_b64_e32 v[98:99], v[2:3]
	v_mov_b64_e32 v[92:93], v[0:1]
	v_mov_b64_e32 v[96:97], v[0:1]
	s_and_saveexec_b64 s[12:13], vcc
	s_cbranch_execz .LBB0_494
	v_or_b32_e32 v0, 24, v135
	v_mul_hi_i32_i24_e32 v3, s90, v0
	v_mul_i32_i24_e32 v2, s90, v0
	v_lshl_add_u64 v[2:3], v[2:3], 2, s[14:15]
	v_lshl_add_u64 v[2:3], v[136:137], 2, v[2:3]
	v_lshl_add_u64 v[96:97], s[90:91], 2, v[2:3]
	global_load_dwordx4 v[92:95], v[2:3], off nt
	s_nop 0
	global_load_dwordx4 v[96:99], v[96:97], off nt
.LBB0_494:
	s_or_b64 exec, exec, s[12:13]
	v_mov_b32_e32 v2, v1
	v_mov_b32_e32 v3, v1
	v_mov_b32_e32 v0, v1
	v_mov_b64_e32 v[102:103], v[2:3]
	v_mov_b64_e32 v[106:107], v[2:3]
	v_mov_b64_e32 v[100:101], v[0:1]
	v_mov_b64_e32 v[104:105], v[0:1]
	s_and_saveexec_b64 s[12:13], vcc
	s_cbranch_execz .LBB0_496
	v_or_b32_e32 v100, 32, v135
	v_mul_hi_i32_i24_e32 v101, s90, v100
	v_mul_i32_i24_e32 v100, s90, v100
	v_lshl_add_u64 v[100:101], v[100:101], 2, s[14:15]
	v_lshl_add_u64 v[100:101], v[136:137], 2, v[100:101]
	v_lshl_add_u64 v[104:105], s[90:91], 2, v[100:101]
	global_load_dwordx4 v[100:103], v[100:101], off nt
	s_nop 0
	global_load_dwordx4 v[104:107], v[104:105], off nt
.LBB0_496:
	s_or_b64 exec, exec, s[12:13]
	v_mov_b64_e32 v[110:111], v[2:3]
	v_mov_b64_e32 v[114:115], v[2:3]
	v_mov_b64_e32 v[108:109], v[0:1]
	v_mov_b64_e32 v[112:113], v[0:1]
	s_and_saveexec_b64 s[12:13], vcc
	s_cbranch_execz .LBB0_498
	v_or_b32_e32 v0, 40, v135
	v_mul_hi_i32_i24_e32 v3, s90, v0
	v_mul_i32_i24_e32 v2, s90, v0
	v_lshl_add_u64 v[2:3], v[2:3], 2, s[14:15]
	v_lshl_add_u64 v[2:3], v[136:137], 2, v[2:3]
	v_lshl_add_u64 v[112:113], s[90:91], 2, v[2:3]
	global_load_dwordx4 v[108:111], v[2:3], off nt
	s_nop 0
	global_load_dwordx4 v[112:115], v[112:113], off nt
.LBB0_498:
	s_or_b64 exec, exec, s[12:13]
	v_mov_b32_e32 v2, v1
	v_mov_b32_e32 v3, v1
	v_mov_b32_e32 v0, v1
	v_mov_b64_e32 v[118:119], v[2:3]
	v_mov_b64_e32 v[122:123], v[2:3]
	v_mov_b64_e32 v[116:117], v[0:1]
	v_mov_b64_e32 v[120:121], v[0:1]
	s_and_saveexec_b64 s[12:13], vcc
	s_cbranch_execz .LBB0_500
	v_or_b32_e32 v116, 48, v135
	v_mul_hi_i32_i24_e32 v117, s90, v116
	v_mul_i32_i24_e32 v116, s90, v116
	v_lshl_add_u64 v[116:117], v[116:117], 2, s[14:15]
	v_lshl_add_u64 v[116:117], v[136:137], 2, v[116:117]
	v_lshl_add_u64 v[120:121], s[90:91], 2, v[116:117]
	global_load_dwordx4 v[116:119], v[116:117], off nt
	s_nop 0
	global_load_dwordx4 v[120:123], v[120:121], off nt
.LBB0_500:
	s_or_b64 exec, exec, s[12:13]
	v_mov_b64_e32 v[126:127], v[2:3]
	v_mov_b64_e32 v[130:131], v[2:3]
	v_mov_b64_e32 v[124:125], v[0:1]
	v_mov_b64_e32 v[128:129], v[0:1]
	s_and_saveexec_b64 s[12:13], vcc
	s_cbranch_execz .LBB0_502
	v_or_b32_e32 v0, 56, v135
	v_mul_hi_i32_i24_e32 v3, s90, v0
	v_mul_i32_i24_e32 v2, s90, v0
	v_lshl_add_u64 v[2:3], v[2:3], 2, s[14:15]
	v_lshl_add_u64 v[2:3], v[136:137], 2, v[2:3]
	v_lshl_add_u64 v[128:129], s[90:91], 2, v[2:3]
	global_load_dwordx4 v[124:127], v[2:3], off nt
	s_nop 0
	global_load_dwordx4 v[128:131], v[128:129], off nt

; #define LDS_FENCE() asm volatile("s_waitcnt vmcnt(0) lgkmcnt(0)" ::: "memory")
; __device__ __forceinline__ unsigned pkh(float lo, float hi) { f32v2_t v; v.x = lo; v.y = hi; return __builtin_bit_cast(unsigned, __builtin_convertvector(v, bf16v2_t)); }
; __device__ __forceinline__ void titem_store(const TItem& t, const TRegs& R, float* scrf, int lane) {
;     unsigned* scr = (unsigned*)scrf;
;     const int nblk = (t.N + 63) / 64, kb = t.item / nblk, nb = t.item % nblk, k0 = 64 * kb, n0 = 64 * nb;
;     const int rg = lane >> 4, c4 = lane & 15;
; #pragma unroll
;     for (int i = 0; i < 8; ++i) { unsigned* q = scr + (4 * i + rg) * 66 + 4 * c4;
;         q[0] = pkh(R.v0[i].x, R.v1[i].x); q[1] = pkh(R.v0[i].y, R.v1[i].y); q[2] = pkh(R.v0[i].z, R.v1[i].z); q[3] = pkh(R.v0[i].w, R.v1[i].w); }
;     LDS_FENCE();
;     const int c = lane & 7;
; #pragma unroll
;     for (int j = 0; j < 8; ++j) { const int n = (lane >> 3) + 8 * j; const unsigned* s = scr + (4 * c) * 66 + n;
;         u32x4 o; o.x = s[0]; o.y = s[66]; o.z = s[132]; o.w = s[198];
;         *(u32x4*)(t.WT + (size_t)(n0 + n) * t.pitch + k0 + 8 * c) = o; }
;     LDS_FENCE();
.LBB0_503:
	s_add_i32 s12, s4, 63
	s_lshr_b32 s13, s12, 6
	s_abs_i32 s15, s13
	v_cvt_f32_u32_e32 v0, s15
	v_cvt_pk_bf16_f32 v2, v9, v5
	s_sub_i32 s16, 0, s15
	v_cvt_pk_bf16_f32 v3, v17, v13
	v_rcp_iflag_f32_e32 v0, v0
	s_abs_i32 s14, s34
	s_xor_b32 s12, s34, s13
	s_ashr_i32 s12, s12, 31
	v_mul_f32_e32 v0, 0x4f7ffffe, v0
	v_cvt_u32_f32_e32 v0, v0
	v_mov_b32_e32 v135, v1
	v_readfirstlane_b32 s17, v0
	v_cvt_pk_bf16_f32 v0, v8, v4
	ds_write2_b32 v148, v0, v2 offset1:1
	v_cvt_pk_bf16_f32 v0, v10, v6
	v_cvt_pk_bf16_f32 v2, v11, v7
	ds_write2_b32 v148, v0, v2 offset0:2 offset1:3
	v_cvt_pk_bf16_f32 v0, v16, v12
	v_add_u32_e32 v2, 0x420, v148
	s_mul_i32 s16, s16, s17
	ds_write2_b32 v2, v0, v3 offset1:1
	v_cvt_pk_bf16_f32 v0, v18, v14
	v_add_u32_e32 v2, 0x428, v148
	v_cvt_pk_bf16_f32 v3, v19, v15
	s_mul_hi_u32 s16, s17, s16
	ds_write2_b32 v2, v0, v3 offset1:1
	v_cvt_pk_bf16_f32 v0, v24, v20
	v_add_u32_e32 v2, 0x840, v148
	v_cvt_pk_bf16_f32 v3, v25, v21
	s_add_i32 s17, s17, s16
	ds_write2_b32 v2, v0, v3 offset1:1
	v_cvt_pk_bf16_f32 v0, v26, v22
	v_add_u32_e32 v2, 0x848, v148
	v_cvt_pk_bf16_f32 v3, v27, v23
	s_mul_hi_u32 s16, s14, s17
	ds_write2_b32 v2, v0, v3 offset1:1
	v_cvt_pk_bf16_f32 v0, v32, v28
	v_add_u32_e32 v2, 0xc60, v148
	v_cvt_pk_bf16_f32 v3, v33, v29
	s_mul_i32 s17, s16, s15
	ds_write2_b32 v2, v0, v3 offset1:1
	v_cvt_pk_bf16_f32 v0, v34, v30
	v_add_u32_e32 v2, 0xc68, v148
	v_cvt_pk_bf16_f32 v3, v35, v31
	s_sub_i32 s14, s14, s17
	ds_write2_b32 v2, v0, v3 offset1:1
	v_cvt_pk_bf16_f32 v0, v40, v36
	v_add_u32_e32 v2, 0x1080, v148
	v_cvt_pk_bf16_f32 v3, v41, v37
	s_add_i32 s17, s16, 1
	s_sub_i32 s18, s14, s15
	ds_write2_b32 v2, v0, v3 offset1:1
	v_cvt_pk_bf16_f32 v0, v42, v38
	v_add_u32_e32 v2, 0x1088, v148
	v_cvt_pk_bf16_f32 v3, v43, v39
	s_cmp_ge_u32 s14, s15
	ds_write2_b32 v2, v0, v3 offset1:1
	v_cvt_pk_bf16_f32 v0, v48, v44
	v_add_u32_e32 v2, 0x14a0, v148
	v_cvt_pk_bf16_f32 v3, v49, v45
	s_cselect_b32 s16, s17, s16
	ds_write2_b32 v2, v0, v3 offset1:1
	v_cvt_pk_bf16_f32 v0, v50, v46
	v_add_u32_e32 v2, 0x14a8, v148
	v_cvt_pk_bf16_f32 v3, v51, v47
	s_cselect_b32 s14, s18, s14
	s_add_i32 s17, s16, 1
	ds_write2_b32 v2, v0, v3 offset1:1
	v_cvt_pk_bf16_f32 v0, v56, v52
	v_add_u32_e32 v2, 0x18c0, v148
	v_cvt_pk_bf16_f32 v3, v57, v53
	s_cmp_ge_u32 s14, s15
	ds_write2_b32 v2, v0, v3 offset1:1
	v_cvt_pk_bf16_f32 v0, v58, v54
	v_add_u32_e32 v2, 0x18c8, v148
	v_cvt_pk_bf16_f32 v3, v59, v55
	s_cselect_b32 s14, s17, s16
	ds_write2_b32 v2, v0, v3 offset1:1
	v_cvt_pk_bf16_f32 v0, v64, v60
	v_add_u32_e32 v2, 0x1ce0, v148
	v_cvt_pk_bf16_f32 v3, v65, v61
	s_xor_b32 s14, s14, s12
	ds_write2_b32 v2, v0, v3 offset1:1
	v_cvt_pk_bf16_f32 v0, v66, v62
	v_add_u32_e32 v2, 0x1ce8, v148
	v_cvt_pk_bf16_f32 v3, v67, v63
	s_sub_i32 s14, s14, s12
	ds_write2_b32 v2, v0, v3 offset1:1
	s_lshl_b32 s12, s14, 6
	s_mul_i32 s14, s14, s13
	s_waitcnt lgkmcnt(0)
	s_sub_i32 s13, s34, s14
	ds_read2_b32 v[150:151], v140 offset0:66 offset1:74
	ds_read2_b32 v[2:3], v140 offset0:132 offset1:140
	ds_read2_b32 v[152:153], v140 offset0:198 offset1:206
	ds_read2_b32 v[136:137], v140 offset1:8
	s_lshl_b32 s14, s13, 6
	v_or_b32_e32 v0, s14, v138
	v_mad_u64_u32 v[158:159], s[16:17], v0, s35, 0
	s_ashr_i32 s15, s14, 31
	v_or_b32_e32 v0, s14, v141
	s_waitcnt lgkmcnt(2)
	v_mov_b32_e32 v156, v2
	s_waitcnt lgkmcnt(1)
	v_mov_b32_e32 v157, v152
	s_mul_i32 s18, s15, s35
	v_mov_b32_e32 v152, v3
	v_mad_u64_u32 v[2:3], s[16:17], v0, s35, 0
	s_ashr_i32 s13, s12, 31
	v_add_u32_e32 v159, s18, v159
	v_add_u32_e32 v3, s18, v3
	v_lshl_add_u64 v[158:159], v[158:159], 1, s[0:1]
	s_lshl_b64 s[12:13], s[12:13], 1
	v_lshl_add_u64 v[2:3], v[2:3], 1, s[0:1]
	v_lshl_add_u64 v[158:159], v[158:159], 0, s[12:13]
	v_lshl_add_u64 v[2:3], v[2:3], 0, s[12:13]
	s_waitcnt lgkmcnt(0)
	v_mov_b32_e32 v154, v136
	v_mov_b32_e32 v155, v150
	v_lshl_add_u64 v[158:159], v[158:159], 0, v[134:135]
	v_mov_b32_e32 v150, v137
	v_lshl_add_u64 v[2:3], v[2:3], 0, v[134:135]
	global_store_dwordx4 v[158:159], v[154:157], off nt
	global_store_dwordx4 v[2:3], v[150:153], off nt
	ds_read2_b32 v[2:3], v140 offset0:16 offset1:24
	ds_read2_b32 v[150:151], v140 offset0:82 offset1:90
	ds_read2_b32 v[136:137], v140 offset0:148 offset1:156
	ds_read2_b32 v[152:153], v140 offset0:214 offset1:222
	v_or_b32_e32 v0, s14, v142
	v_mad_u64_u32 v[158:159], s[16:17], v0, s35, 0
	v_or_b32_e32 v0, s14, v143
	s_waitcnt lgkmcnt(3)
; #define LDS_FENCE() asm volatile("s_waitcnt vmcnt(0) lgkmcnt(0)" ::: "memory")
; __device__ __forceinline__ unsigned pkh(float lo, float hi) { f32v2_t v; v.x = lo; v.y = hi; return __builtin_bit_cast(unsigned, __builtin_convertvector(v, bf16v2_t)); }
; __device__ __forceinline__ void titem_store(const TItem& t, const TRegs& R, float* scrf, int lane) {
;     ...
;         q[0] = pkh(R.v0[i].x, R.v1[i].x); q[1] = pkh(R.v0[i].y, R.v1[i].y); q[2] = pkh(R.v0[i].z, R.v1[i].z); q[3] = pkh(R.v0[i].w, R.v1[i].w); }
;     LDS_FENCE();
;     const int c = lane & 7;
; #pragma unroll
;     for (int j = 0; j < 8; ++j) { const int n = (lane >> 3) + 8 * j; const unsigned* s = scr + (4 * c) * 66 + n;
;         u32x4 o; o.x = s[0]; o.y = s[66]; o.z = s[132]; o.w = s[198];
;         *(u32x4*)(t.WT + (size_t)(n0 + n) * t.pitch + k0 + 8 * c) = o; }
;     LDS_FENCE();
; __device__ __forceinline__ void phase_prologue(const PT a, float* ldsf, int lane, int wave, int gw, int ngw) {
;     ...
;             TItem nxt = cur; TRegs R2 = R;
;             if (more) { nxt = decode_item(a, ws, nx); titem_load(nxt, R2, lane); }
;             titem_store(cur, R, scr, lane);
;             if (!more) break;
;             cur = nxt; R = R2; it = nx;
;         }
	v_mov_b32_e32 v154, v2
	s_waitcnt lgkmcnt(2)
	v_mov_b32_e32 v155, v150
	v_mov_b32_e32 v150, v3
	v_mad_u64_u32 v[2:3], s[16:17], v0, s35, 0
	v_add_u32_e32 v159, s18, v159
	v_add_u32_e32 v3, s18, v3
	v_lshl_add_u64 v[158:159], v[158:159], 1, s[0:1]
	v_lshl_add_u64 v[2:3], v[2:3], 1, s[0:1]
	v_lshl_add_u64 v[158:159], v[158:159], 0, s[12:13]
	v_lshl_add_u64 v[2:3], v[2:3], 0, s[12:13]
	s_waitcnt lgkmcnt(1)
	v_mov_b32_e32 v156, v136
	s_waitcnt lgkmcnt(0)
	v_mov_b32_e32 v157, v152
	v_lshl_add_u64 v[158:159], v[158:159], 0, v[134:135]
	v_mov_b32_e32 v152, v137
	v_lshl_add_u64 v[2:3], v[2:3], 0, v[134:135]
	global_store_dwordx4 v[158:159], v[154:157], off nt
	global_store_dwordx4 v[2:3], v[150:153], off nt
	ds_read2_b32 v[2:3], v140 offset0:32 offset1:40
	ds_read2_b32 v[150:151], v140 offset0:98 offset1:106
	ds_read2_b32 v[136:137], v140 offset0:164 offset1:172
	ds_read2_b32 v[152:153], v140 offset0:230 offset1:238
	v_or_b32_e32 v0, s14, v144
	v_mad_u64_u32 v[158:159], s[16:17], v0, s35, 0
	v_or_b32_e32 v0, s14, v145
	s_waitcnt lgkmcnt(3)
	v_mov_b32_e32 v154, v2
	s_waitcnt lgkmcnt(2)
	v_mov_b32_e32 v155, v150
	v_mov_b32_e32 v150, v3
	v_mad_u64_u32 v[2:3], s[16:17], v0, s35, 0
	v_add_u32_e32 v159, s18, v159
	v_add_u32_e32 v3, s18, v3
	v_lshl_add_u64 v[158:159], v[158:159], 1, s[0:1]
	v_lshl_add_u64 v[2:3], v[2:3], 1, s[0:1]
	v_lshl_add_u64 v[158:159], v[158:159], 0, s[12:13]
	v_lshl_add_u64 v[2:3], v[2:3], 0, s[12:13]
	s_waitcnt lgkmcnt(1)
	v_mov_b32_e32 v156, v136
	s_waitcnt lgkmcnt(0)
	v_mov_b32_e32 v157, v152
	v_lshl_add_u64 v[158:159], v[158:159], 0, v[134:135]
	v_mov_b32_e32 v152, v137
	v_lshl_add_u64 v[2:3], v[2:3], 0, v[134:135]
	global_store_dwordx4 v[158:159], v[154:157], off nt
	global_store_dwordx4 v[2:3], v[150:153], off nt
	ds_read2_b32 v[2:3], v140 offset0:48 offset1:56
	ds_read2_b32 v[150:151], v140 offset0:114 offset1:122
	ds_read2_b32 v[136:137], v140 offset0:180 offset1:188
	ds_read2_b32 v[152:153], v140 offset0:246 offset1:254
	v_or_b32_e32 v0, s14, v146
	v_mad_u64_u32 v[158:159], s[16:17], v0, s35, 0
	v_or_b32_e32 v0, s14, v147
	s_waitcnt lgkmcnt(3)
	v_mov_b32_e32 v154, v2
	s_waitcnt lgkmcnt(2)
	v_mov_b32_e32 v155, v150
	v_mov_b32_e32 v150, v3
	v_mad_u64_u32 v[2:3], s[14:15], v0, s35, 0
	v_add_u32_e32 v159, s18, v159
	v_add_u32_e32 v3, s18, v3
	v_lshl_add_u64 v[158:159], v[158:159], 1, s[0:1]
	v_lshl_add_u64 v[2:3], v[2:3], 1, s[0:1]
	v_lshl_add_u64 v[158:159], v[158:159], 0, s[12:13]
	v_lshl_add_u64 v[2:3], v[2:3], 0, s[12:13]
	s_waitcnt lgkmcnt(1)
	v_mov_b32_e32 v156, v136
	s_waitcnt lgkmcnt(0)
	v_mov_b32_e32 v157, v152
	v_lshl_add_u64 v[158:159], v[158:159], 0, v[134:135]
	v_mov_b32_e32 v152, v137
	v_lshl_add_u64 v[2:3], v[2:3], 0, v[134:135]
	global_store_dwordx4 v[158:159], v[154:157], off nt
	global_store_dwordx4 v[2:3], v[150:153], off nt
	s_waitcnt lgkmcnt(0)
	s_andn2_b64 vcc, exec, s[8:9]
	s_cbranch_vccnz .LBB0_445
	s_waitcnt vmcnt(8)
	v_mov_b64_e32 v[60:61], v[128:129]
	v_mov_b64_e32 v[52:53], v[120:121]
	v_mov_b64_e32 v[44:45], v[112:113]
	v_mov_b64_e32 v[36:37], v[104:105]
	v_mov_b64_e32 v[28:29], v[96:97]
	v_mov_b64_e32 v[20:21], v[88:89]
	v_mov_b64_e32 v[12:13], v[80:81]
	v_mov_b64_e32 v[4:5], v[72:73]
	v_mov_b64_e32 v[64:65], v[124:125]
	v_mov_b64_e32 v[56:57], v[116:117]
	v_mov_b64_e32 v[48:49], v[108:109]
	v_mov_b64_e32 v[40:41], v[100:101]
	v_mov_b64_e32 v[32:33], v[92:93]
	v_mov_b64_e32 v[24:25], v[84:85]
	v_mov_b64_e32 v[16:17], v[76:77]
	v_mov_b64_e32 v[8:9], v[68:69]
	s_mov_b32 s35, s24
	s_mov_b32 s34, s37
	s_mov_b32 s4, s90
	s_mov_b64 s[0:1], s[10:11]
	v_mov_b64_e32 v[62:63], v[130:131]
	v_mov_b64_e32 v[54:55], v[122:123]
	v_mov_b64_e32 v[46:47], v[114:115]
	v_mov_b64_e32 v[38:39], v[106:107]
	v_mov_b64_e32 v[30:31], v[98:99]
	v_mov_b64_e32 v[22:23], v[90:91]
	v_mov_b64_e32 v[14:15], v[82:83]
	v_mov_b64_e32 v[6:7], v[74:75]
	v_mov_b64_e32 v[66:67], v[126:127]
	v_mov_b64_e32 v[58:59], v[118:119]
	v_mov_b64_e32 v[50:51], v[110:111]
	v_mov_b64_e32 v[42:43], v[102:103]
	v_mov_b64_e32 v[34:35], v[94:95]
	v_mov_b64_e32 v[26:27], v[86:87]
	v_mov_b64_e32 v[18:19], v[78:79]
	v_mov_b64_e32 v[10:11], v[70:71]
	s_mov_b32 s5, s36
	s_branch .LBB0_445
